# v43 + prep: the barrier before the q/k/v maps moved after the first block's weight loads (they do not depend on the LDS tiles it guards)
# baseline (speedup 1.0000x reference)
; DI void prep_phase(PARAMS P, int l, int g, LAS unsigned char* lds, int wave, int lane) {
;     ...
;         }
;         __syncthreads();
;         {
;             const int r = lane & 31, hh = lane >> 5;
; #pragma unroll 1
;             for (int cbk = wave * 6; cbk < wave * 6 + 6; ++cbk) {
.LBB0_743:
	s_or_b32 s2, s6, 32
	s_lshl_b32 s3, s64, 2
	s_mov_b32 s7, 0
	s_mov_b32 s16, s61
	s_branch .LBB0_746

; #define LAS __attribute__((address_space(3)))
; #define MFMA32(a, b, c) __builtin_amdgcn_mfma_f32_32x32x16_bf16((a), (b), (c), 0, 0, 0)
; DI void prep_phase(PARAMS P, int l, int g, LAS unsigned char* lds, int wave, int lane) {
;     ...
;             for (int cbk = wave * 6; cbk < wave * 6 + 6; ++cbk) {
;                 const int mt = cbk >> 4, hd = (cbk >> 2) & 3, nb = cbk & 3;
;                 const bf16_t* wt = wm + (size_t)(mt * 4 + hd) * 16384 + (size_t)(32 * nb + r) * 128 + 8 * hh;
;                 const LAS bf16_t* al = (mt == 2 ? Xl : Cl) + r * 520 + hd * 128 + 8 * hh;
;                 f32x16 a0, a1;
; #pragma unroll
;                 for (int i = 0; i < 16; ++i) { a0[i] = 0.f; a1[i] = 0.f; }
; #pragma unroll
;                 for (int ks = 0; ks < 8; ++ks) {
;                     const bf16x8 b = *(const bf16x8*)(wt + 16 * ks);
;                     const bf16x8 x0 = *(const LAS bf16x8*)(al + 16 * ks), x1 = *(const LAS bf16x8*)(al + 32 * 520 + 16 * ks);
;                     a0 = MFMA32(x0, b, a0); a1 = MFMA32(x1, b, a1);
;                 }
.LBB0_746:
	s_lshr_b32 s33, s7, 1
	s_lshl_b32 s33, s33, 4
	s_and_b32 s98, s7, 1
	s_add_i32 s33, s33, s98
	s_add_i32 s33, s33, s60
	s_ashr_i32 s64, s33, 4
	s_bfe_u32 s17, s33, 0x20002
	s_lshl_b32 s4, s64, 2
	s_or_b32 s4, s4, s17
	s_ashr_i32 s5, s4, 31
	s_lshl_b64 s[4:5], s[4:5], 15
	s_add_u32 s4, s19, s4
	s_addc_u32 s5, s35, s5
	s_and_b32 s20, s33, 3
	s_lshl_b32 s20, s20, 5
	v_or_b32_e32 v125, s20, v35
	v_lshlrev_b32_e32 v32, 8, v125
	s_waitcnt lgkmcnt(0)
	v_lshl_add_u64 v[0:1], s[4:5], 0, v[32:33]
	v_mov_b32_e32 v87, v33
	v_lshl_add_u64 v[88:89], v[0:1], 0, v[86:87]
	global_load_dwordx4 v[16:19], v[88:89], off
	global_load_dwordx4 v[130:133], v[88:89], off offset:32
	global_load_dwordx4 v[140:143], v[88:89], off offset:64
	global_load_dwordx4 v[144:147], v[88:89], off offset:96
	global_load_dwordx4 v[148:151], v[88:89], off offset:128
	global_load_dwordx4 v[152:155], v[88:89], off offset:160
	global_load_dwordx4 v[156:159], v[88:89], off offset:192
	global_load_dwordx4 v[160:163], v[88:89], off offset:224
	s_cmp_lg_u32 s7, 0
	s_cbranch_scc1 .Lmaps_nobar
	s_waitcnt lgkmcnt(0)
	s_barrier
.Lmaps_nobar:
	s_cmp_eq_u32 s64, 2
	s_cselect_b32 s4, s27, 0
	s_lshl_b32 s21, s17, 8
	s_add_i32 s4, s21, s4
	v_add3_u32 v32, s4, v93, v86
	ds_read_b128 v[20:23], v32 offset:33280
	ds_read_b128 v[0:3], v32
	ds_read_b128 v[126:129], v32 offset:32
	ds_read_b128 v[134:137], v32 offset:33312
	s_mov_b64 s[4:5], -1
	s_cmp_lg_u32 s64, 1
	s_waitcnt vmcnt(7) lgkmcnt(2)
	v_mfma_f32_32x32x16_bf16 v[0:15], v[0:3], v[16:19], 0
	s_waitcnt vmcnt(6) lgkmcnt(1)
	v_mfma_f32_32x32x16_bf16 v[0:15], v[126:129], v[130:133], v[0:15]
	v_mfma_f32_32x32x16_bf16 v[16:31], v[20:23], v[16:19], 0
	s_waitcnt lgkmcnt(0)
	v_mfma_f32_32x32x16_bf16 v[16:31], v[134:137], v[130:133], v[16:31]
	ds_read_b128 v[130:133], v32 offset:64
	ds_read_b128 v[134:137], v32 offset:33344
	s_waitcnt vmcnt(5) lgkmcnt(1)
	v_mfma_f32_32x32x16_bf16 v[0:15], v[130:133], v[140:143], v[0:15]
	s_waitcnt lgkmcnt(0)
	v_mfma_f32_32x32x16_bf16 v[16:31], v[134:137], v[140:143], v[16:31]
	ds_read_b128 v[130:133], v32 offset:96
	ds_read_b128 v[134:137], v32 offset:33376
	s_waitcnt vmcnt(4) lgkmcnt(1)
	v_mfma_f32_32x32x16_bf16 v[0:15], v[130:133], v[144:147], v[0:15]
	s_waitcnt lgkmcnt(0)
	v_mfma_f32_32x32x16_bf16 v[16:31], v[134:137], v[144:147], v[16:31]
	ds_read_b128 v[130:133], v32 offset:128
	ds_read_b128 v[134:137], v32 offset:33408
	s_waitcnt vmcnt(3) lgkmcnt(1)
	v_mfma_f32_32x32x16_bf16 v[0:15], v[130:133], v[148:151], v[0:15]
	s_waitcnt lgkmcnt(0)
	v_mfma_f32_32x32x16_bf16 v[16:31], v[134:137], v[148:151], v[16:31]
	ds_read_b128 v[130:133], v32 offset:160
	ds_read_b128 v[134:137], v32 offset:33440
	s_waitcnt vmcnt(2) lgkmcnt(1)
	v_mfma_f32_32x32x16_bf16 v[0:15], v[130:133], v[152:155], v[0:15]
	s_waitcnt lgkmcnt(0)
	v_mfma_f32_32x32x16_bf16 v[16:31], v[134:137], v[152:155], v[16:31]
	ds_read_b128 v[130:133], v32 offset:192
	ds_read_b128 v[134:137], v32 offset:33472
	s_waitcnt vmcnt(1) lgkmcnt(1)
	v_mfma_f32_32x32x16_bf16 v[0:15], v[130:133], v[156:159], v[0:15]
	s_waitcnt lgkmcnt(0)
	v_mfma_f32_32x32x16_bf16 v[16:31], v[134:137], v[156:159], v[16:31]
	ds_read_b128 v[130:133], v32 offset:224
	ds_read_b128 v[134:137], v32 offset:33504
	v_lshl_or_b32 v32, s17, 7, v125
	v_lshlrev_b32_e32 v32, 1, v32
	s_waitcnt vmcnt(0) lgkmcnt(1)
	v_mfma_f32_32x32x16_bf16 v[0:15], v[130:133], v[160:163], v[0:15]
	s_waitcnt lgkmcnt(0)
	v_mfma_f32_32x32x16_bf16 v[16:31], v[134:137], v[160:163], v[16:31]
	s_cbranch_scc1 .LBB0_748
	s_andn2_b64 vcc, exec, s[4:5]
	s_cbranch_vccnz .LBB0_745
	s_branch .LBB0_749
